# attention rel-pos bias block rewritten: 16 bias loads in flight together, branch-free masking (was 16 serialized load+wait with exec branches)
# speedup vs baseline: 1.0697x; 1.0109x over previous
.LBB0_401:
	s_or_b64 exec, exec, s[8:9]
	ds_read_b128 v[32:35], v147
	ds_read_b128 v[48:51], v147 offset:32
	s_cmp_gt_u32 s65, 15
	s_cselect_b64 s[8:9], -1, 0
	s_and_b64 s[8:9], s[42:43], s[8:9]
	s_waitcnt lgkmcnt(1)
	v_mfma_f32_32x32x16_bf16 v[32:47], v[32:35], v[64:67], 0
	s_waitcnt lgkmcnt(0)
	v_mfma_f32_32x32x16_bf16 v[32:47], v[48:51], v[68:71], v[32:47]
	ds_read_b128 v[48:51], v147 offset:64
	ds_read_b128 v[52:55], v147 offset:96
	s_waitcnt lgkmcnt(1)
	v_mfma_f32_32x32x16_bf16 v[32:47], v[48:51], v[72:75], v[32:47]
	s_waitcnt lgkmcnt(0)
	v_mfma_f32_32x32x16_bf16 v[32:47], v[52:55], v[76:79], v[32:47]
	s_and_saveexec_b64 s[44:45], s[8:9]
	s_cbranch_execz .LBB0_392
	s_add_i32 s9, s65, -16
	s_ashr_i32 s9, s9, 1
	s_sub_i32 s8, s63, 32
	v_add_u32_e32 v48, s9, v152
	v_and_or_b32 v112, s8, 32, v145
	v_mad_u64_u32 v[140:141], s[8:9], v48, 31, v[120:121]
	v_subrev_u32_e32 v207, s14, v132
	v_add_u32_e32 v140, 15, v140
	v_mov_b32_e32 v210, 0xf149f2ca
	v_lshl_add_u32 v207, v140, 2, v207
	v_or_b32_e32 v208, 0, v112
	v_sub_u32_e32 v209, v208, v151
	v_med3_i32 v209, v209, -15, 15
	v_lshl_add_u32 v209, v209, 2, v207
	global_load_dword v190, v209, s[14:15]
	v_or_b32_e32 v208, 1, v112
	v_sub_u32_e32 v209, v208, v151
	v_med3_i32 v209, v209, -15, 15
	v_lshl_add_u32 v209, v209, 2, v207
	global_load_dword v191, v209, s[14:15]
	v_or_b32_e32 v208, 2, v112
	v_sub_u32_e32 v209, v208, v151
	v_med3_i32 v209, v209, -15, 15
	v_lshl_add_u32 v209, v209, 2, v207
	global_load_dword v192, v209, s[14:15]
	v_or_b32_e32 v208, 3, v112
	v_sub_u32_e32 v209, v208, v151
	v_med3_i32 v209, v209, -15, 15
	v_lshl_add_u32 v209, v209, 2, v207
	global_load_dword v193, v209, s[14:15]
	v_or_b32_e32 v208, 8, v112
	v_sub_u32_e32 v209, v208, v151
	v_med3_i32 v209, v209, -15, 15
	v_lshl_add_u32 v209, v209, 2, v207
	global_load_dword v194, v209, s[14:15]
	v_or_b32_e32 v208, 9, v112
	v_sub_u32_e32 v209, v208, v151
	v_med3_i32 v209, v209, -15, 15
	v_lshl_add_u32 v209, v209, 2, v207
	global_load_dword v195, v209, s[14:15]
	v_or_b32_e32 v208, 10, v112
	v_sub_u32_e32 v209, v208, v151
	v_med3_i32 v209, v209, -15, 15
	v_lshl_add_u32 v209, v209, 2, v207
	global_load_dword v196, v209, s[14:15]
	v_or_b32_e32 v208, 11, v112
	v_sub_u32_e32 v209, v208, v151
	v_med3_i32 v209, v209, -15, 15
	v_lshl_add_u32 v209, v209, 2, v207
	global_load_dword v197, v209, s[14:15]
	v_or_b32_e32 v208, 16, v112
	v_sub_u32_e32 v209, v208, v151
	v_med3_i32 v209, v209, -15, 15
	v_lshl_add_u32 v209, v209, 2, v207
	global_load_dword v198, v209, s[14:15]
	v_or_b32_e32 v208, 17, v112
	v_sub_u32_e32 v209, v208, v151
	v_med3_i32 v209, v209, -15, 15
	v_lshl_add_u32 v209, v209, 2, v207
	global_load_dword v199, v209, s[14:15]
	v_or_b32_e32 v208, 18, v112
	v_sub_u32_e32 v209, v208, v151
	v_med3_i32 v209, v209, -15, 15
	v_lshl_add_u32 v209, v209, 2, v207
	global_load_dword v200, v209, s[14:15]
	v_or_b32_e32 v208, 19, v112
	v_sub_u32_e32 v209, v208, v151
	v_med3_i32 v209, v209, -15, 15
	v_lshl_add_u32 v209, v209, 2, v207
	global_load_dword v201, v209, s[14:15]
	v_or_b32_e32 v208, 24, v112
	v_sub_u32_e32 v209, v208, v151
	v_med3_i32 v209, v209, -15, 15
	v_lshl_add_u32 v209, v209, 2, v207
	global_load_dword v202, v209, s[14:15]
	v_or_b32_e32 v208, 25, v112
	v_sub_u32_e32 v209, v208, v151
	v_med3_i32 v209, v209, -15, 15
	v_lshl_add_u32 v209, v209, 2, v207
	global_load_dword v203, v209, s[14:15]
	v_or_b32_e32 v208, 26, v112
	v_sub_u32_e32 v209, v208, v151
	v_med3_i32 v209, v209, -15, 15
	v_lshl_add_u32 v209, v209, 2, v207
	global_load_dword v204, v209, s[14:15]
	v_or_b32_e32 v208, 27, v112
	v_sub_u32_e32 v209, v208, v151
	v_med3_i32 v209, v209, -15, 15
	v_lshl_add_u32 v209, v209, 2, v207
	global_load_dword v205, v209, s[14:15]
	v_or_b32_e32 v208, 0, v112
	v_sub_u32_e32 v208, v208, v153
	v_cmp_gt_u32_e32 vcc, 16, v208
	s_waitcnt vmcnt(0)
	v_fmamk_f32 v48, v190, 0x3fb8aa3b, v32
	v_or_b32_e32 v211, 1, v112
	v_sub_u32_e32 v211, v211, v153
	v_cmp_gt_u32_e64 s[46:47], 16, v211
	v_cndmask_b32_e32 v48, v210, v48, vcc
	v_fmamk_f32 v49, v191, 0x3fb8aa3b, v33
	v_or_b32_e32 v208, 2, v112
	v_sub_u32_e32 v208, v208, v153
	v_cmp_gt_u32_e32 vcc, 16, v208
	v_cndmask_b32_e64 v49, v210, v49, s[46:47]
	v_fmamk_f32 v50, v192, 0x3fb8aa3b, v34
	v_or_b32_e32 v211, 3, v112
	v_sub_u32_e32 v211, v211, v153
	v_cmp_gt_u32_e64 s[46:47], 16, v211
	v_cndmask_b32_e32 v50, v210, v50, vcc
	v_fmamk_f32 v51, v193, 0x3fb8aa3b, v35
	v_or_b32_e32 v208, 8, v112
	v_sub_u32_e32 v208, v208, v153
	v_cmp_gt_u32_e32 vcc, 16, v208
	v_cndmask_b32_e64 v51, v210, v51, s[46:47]
	v_fmamk_f32 v52, v194, 0x3fb8aa3b, v36
	v_or_b32_e32 v211, 9, v112
	v_sub_u32_e32 v211, v211, v153
	v_cmp_gt_u32_e64 s[46:47], 16, v211
	v_cndmask_b32_e32 v52, v210, v52, vcc
	v_fmamk_f32 v53, v195, 0x3fb8aa3b, v37
	v_or_b32_e32 v208, 10, v112
	v_sub_u32_e32 v208, v208, v153
	v_cmp_gt_u32_e32 vcc, 16, v208
	v_cndmask_b32_e64 v53, v210, v53, s[46:47]
	v_fmamk_f32 v54, v196, 0x3fb8aa3b, v38
	v_or_b32_e32 v211, 11, v112
	v_sub_u32_e32 v211, v211, v153
	v_cmp_gt_u32_e64 s[46:47], 16, v211
	v_cndmask_b32_e32 v54, v210, v54, vcc
	v_fmamk_f32 v55, v197, 0x3fb8aa3b, v39
	v_or_b32_e32 v208, 16, v112
	v_sub_u32_e32 v208, v208, v153
	v_cmp_gt_u32_e32 vcc, 16, v208
	v_cndmask_b32_e64 v55, v210, v55, s[46:47]
	v_fmamk_f32 v56, v198, 0x3fb8aa3b, v40
	v_or_b32_e32 v211, 17, v112
	v_sub_u32_e32 v211, v211, v153
	v_cmp_gt_u32_e64 s[46:47], 16, v211
	v_cndmask_b32_e32 v56, v210, v56, vcc
	v_fmamk_f32 v57, v199, 0x3fb8aa3b, v41
	v_or_b32_e32 v208, 18, v112
	v_sub_u32_e32 v208, v208, v153
	v_cmp_gt_u32_e32 vcc, 16, v208
	v_cndmask_b32_e64 v57, v210, v57, s[46:47]
	v_fmamk_f32 v58, v200, 0x3fb8aa3b, v42
	v_or_b32_e32 v211, 19, v112
	v_sub_u32_e32 v211, v211, v153
	v_cmp_gt_u32_e64 s[46:47], 16, v211
	v_cndmask_b32_e32 v58, v210, v58, vcc
	v_fmamk_f32 v59, v201, 0x3fb8aa3b, v43
	v_or_b32_e32 v208, 24, v112
	v_sub_u32_e32 v208, v208, v153
	v_cmp_gt_u32_e32 vcc, 16, v208
	v_cndmask_b32_e64 v59, v210, v59, s[46:47]
	v_fmamk_f32 v60, v202, 0x3fb8aa3b, v44
	v_or_b32_e32 v211, 25, v112
	v_sub_u32_e32 v211, v211, v153
	v_cmp_gt_u32_e64 s[46:47], 16, v211
	v_cndmask_b32_e32 v60, v210, v60, vcc
	v_fmamk_f32 v61, v203, 0x3fb8aa3b, v45
	v_or_b32_e32 v208, 26, v112
	v_sub_u32_e32 v208, v208, v153
	v_cmp_gt_u32_e32 vcc, 16, v208
	v_cndmask_b32_e64 v61, v210, v61, s[46:47]
	v_fmamk_f32 v62, v204, 0x3fb8aa3b, v46
	v_or_b32_e32 v211, 27, v112
	v_sub_u32_e32 v211, v211, v153
	v_cmp_gt_u32_e64 s[46:47], 16, v211
	v_cndmask_b32_e32 v62, v210, v62, vcc
	v_fmamk_f32 v63, v205, 0x3fb8aa3b, v47
	s_nop 0
	v_cndmask_b32_e64 v63, v210, v63, s[46:47]
	s_mov_b64 s[8:9], exec
	s_branch .LBB0_391
